# stack12 + P0 w_in transposition item order permuted (8 kb x 4 nb per 32 consecutive items): 1 KiB-contiguous source row segments across neighbouring workgroups
# baseline (speedup 1.0000x reference)
.LBB0_7:
	s_load_dwordx2 s[88:89], s[80:81], 0x90
	s_lshr_b32 s90, s83, 6
	v_and_b32_e32 v1, 63, v0
	s_waitcnt lgkmcnt(0)
	s_cmp_lt_i32 s88, 1
	s_cselect_b64 s[0:1], -1, 0
	s_cmp_gt_i32 s89, 0
	s_cselect_b64 s[2:3], -1, 0
	s_and_b64 s[2:3], s[0:1], s[2:3]
	s_andn2_b64 vcc, exec, s[2:3]
	s_cbranch_vccnz .LBB0_80
	s_load_dwordx8 s[8:15], s[80:81], 0x0
	s_lshl_b32 s0, s93, 3
	s_add_i32 s16, s0, s90
	s_lshl_b32 s18, s79, 3
	s_lshl_b32 s0, s93, 9
	s_lshl_b32 s6, s79, 9
	s_cmpk_gt_i32 s16, 0x267f
	s_cbranch_scc1 .LBB0_57
	v_lshlrev_b32_e32 v2, 2, v0
	v_and_b32_e32 v72, 60, v2
	v_lshlrev_b32_e32 v2, 3, v0
	v_and_b32_e32 v2, 56, v2
	v_lshlrev_b32_e32 v66, 1, v2
	v_mov_b32_e32 v67, 0
	s_mul_i32 s1, s90, 0x4100
	v_lshrrev_b32_e32 v74, 3, v1
	v_mul_u32_u24_e32 v6, 0x104, v2
	v_lshl_add_u64 v[2:3], s[76:77], 0, v[66:67]
	s_mov_b64 s[4:5], 0x10000
	s_add_i32 s1, s1, 0
	v_lshl_add_u64 v[68:69], v[2:3], 0, s[4:5]
	v_lshlrev_b32_e32 v2, 2, v74
	v_lshl_add_u32 v4, v72, 2, s1
	v_add3_u32 v75, s1, v6, v2
	s_lshl_b32 s1, s93, 8
	s_lshl_b32 s4, s90, 5
	v_lshrrev_b32_e32 v73, 4, v1
	s_add_i32 s1, s1, s4
	s_lshl_b32 s4, s90, 6
	v_mul_u32_u24_e32 v5, 0x104, v73
	s_add_i32 s17, s0, s4
	s_lshl_b32 s4, s93, 4
	s_lshl_b32 s5, s90, 1
	s_mov_b32 s21, 0
	v_or_b32_e32 v76, 8, v74
	v_or_b32_e32 v77, 16, v74
	v_or_b32_e32 v78, 24, v74
	v_or_b32_e32 v79, 32, v74
	v_or_b32_e32 v80, 40, v74
	v_or_b32_e32 v81, 48, v74
	v_or_b32_e32 v82, 56, v74
	s_lshl_b32 s7, s79, 8
	s_add_i32 s19, s4, s5
	s_lshl_b32 s24, s79, 4
	s_movk_i32 s25, 0x13ff
	s_movk_i32 s26, 0x4c30
	s_movk_i32 s27, 0x780
	s_movk_i32 s28, 0x1000
	s_movk_i32 s29, 0x1c30
	s_movk_i32 s30, 0x2c30
	v_add_u32_e32 v83, v4, v5
	s_lshr_b32 s20, s16, 5
	s_and_b32 s20, s20, 3
	s_lshl_b32 s20, s20, 3
	s_and_b32 s22, s16, 7
	s_or_b32 s20, s20, s22
	s_lshr_b32 s22, s16, 7
	s_lshl_b32 s22, s22, 2
	s_lshr_b32 s23, s16, 3
	s_and_b32 s23, s23, 3
	s_or_b32 s22, s22, s23
	s_lshl_b32 s22, s22, 5
	s_or_b32 s31, s22, s20
	s_lshl_b32 s1, s31, 5
	s_lshl_b32 s17, s31, 6
	s_lshl_b32 s19, s31, 1
	s_branch .LBB0_11
